# grid barrier: all waiters poll the cross-XCD arrival counter until it reaches (round+1)*nx; release generation no longer on the critical path
# baseline (speedup 1.0000x reference)
; __device__ __forceinline__ unsigned xb_ld(unsigned* p)              { return __hip_atomic_load(p, __ATOMIC_RELAXED, __HIP_MEMORY_SCOPE_AGENT); }
; __device__ __forceinline__ unsigned xb_add(unsigned* p, unsigned v) { return __hip_atomic_fetch_add(p, v, __ATOMIC_RELAXED, __HIP_MEMORY_SCOPE_AGENT); }
; #define XB_SPIN(cond, bar) do { unsigned _sp = 0; while (cond) { __builtin_amdgcn_s_sleep(1); \
;     if ((++_sp & 255u) == 0u) { if (xb_ld(&(bar)[XB_TMO])) break; if (_sp > XB_SPIN_CAP) { atomicAdd(&(bar)[XB_TMO], 1u); break; } } } } while (0)
; __device__ __forceinline__ void xcd_barrier(const XcdBarrier& b) {
;     ...
;         const unsigned old = xb_add(&bar[XB_XSUB(b.x)], 1u);
;         const unsigned gen = old / nloc;
;         if (old + 1u == (gen + 1u) * nloc) {
;             __builtin_amdgcn_fence(__ATOMIC_RELEASE, "agent");
;             asm volatile("s_waitcnt vmcnt(0)" ::: "memory");
;             const unsigned og = xb_add(&bar[XB_TOP], 1u);
;             const unsigned tg = og / nx;
;             if (og + 1u == (tg + 1u) * nx) xb_add(&bar[XB_TOPGEN], 1u);
;             else XB_SPIN(xb_ld(&bar[XB_TOPGEN]) == tg, bar);
;             __builtin_amdgcn_fence(__ATOMIC_ACQUIRE, "agent");
;             xb_add(&bar[XB_XGEN(b.x)], 1u);
;             asm volatile("s_waitcnt vmcnt(0)" ::: "memory");
;         } else {
;             XB_SPIN(xb_ld(&bar[XB_XGEN(b.x)]) == gen, bar);
;             __builtin_amdgcn_fence(__ATOMIC_ACQUIRE, "agent");
;             asm volatile("s_waitcnt vmcnt(0)" ::: "memory");
;         }
.LBB0_134:
	v_readlane_b32 s4, v254, 9
	s_lshl_b32 s4, s4, 8
	v_readlane_b32 s6, v254, 7
	v_readlane_b32 s7, v254, 8
	s_add_u32 s4, s6, s4
	s_addc_u32 s5, s7, 0
	v_mov_b32_e32 v2, 0x1000
	v_mov_b32_e32 v4, 1
	global_atomic_add v4, v2, v4, s[4:5] offset:1024 sc0
	v_cvt_f32_u32_e32 v2, v3
	v_sub_u32_e32 v5, 0, v3
	v_rcp_iflag_f32_e32 v2, v2
	s_nop 0
	v_mul_f32_e32 v2, 0x4f7ffffe, v2
	v_cvt_u32_f32_e32 v2, v2
	v_mul_lo_u32 v5, v5, v2
	v_mul_hi_u32 v5, v2, v5
	v_add_u32_e32 v2, v2, v5
	s_waitcnt vmcnt(0)
	v_mul_hi_u32 v2, v4, v2
	v_mul_lo_u32 v5, v2, v3
	v_sub_u32_e32 v5, v4, v5
	v_add_u32_e32 v6, 1, v2
	v_cmp_ge_u32_e32 vcc, v5, v3
	v_add_u32_e32 v4, 1, v4
	s_nop 0
	v_cndmask_b32_e32 v2, v2, v6, vcc
	v_sub_u32_e32 v6, v5, v3
	v_cndmask_b32_e32 v5, v5, v6, vcc
	v_add_u32_e32 v6, 1, v2
	v_cmp_ge_u32_e32 vcc, v5, v3
	s_nop 1
	v_cndmask_b32_e32 v2, v2, v6, vcc
	v_mul_lo_u32 v5, v3, v2
	v_add_u32_e32 v3, v5, v3
	v_cmp_ne_u32_e32 vcc, v4, v3
	s_and_saveexec_b64 s[6:7], vcc
	s_xor_b64 s[6:7], exec, s[6:7]
	s_cbranch_execz .LBB0_148
	s_waitcnt lgkmcnt(0)
	v_readlane_b32 s10, v254, 7
	v_readlane_b32 s11, v254, 8
	v_add_u32_e32 v2, 1, v2
	v_mul_lo_u32 v2, v2, v1
	v_mov_b32_e32 v1, 0
	s_add_u32 s10, s10, 0x3400
	s_addc_u32 s11, s11, 0
	global_load_dword v1, v1, s[10:11] sc1
	s_waitcnt vmcnt(0)
	v_cmp_lt_u32_e32 vcc, v1, v2
	s_and_saveexec_b64 s[8:9], vcc
	s_cbranch_execz .LBB0_147
	s_mov_b32 s24, 1
	s_mov_b64 s[14:15], 0
	v_mov_b32_e32 v1, 0
	s_branch .LBB0_138

; __device__ __forceinline__ unsigned xb_ld(unsigned* p)              { return __hip_atomic_load(p, __ATOMIC_RELAXED, __HIP_MEMORY_SCOPE_AGENT); }
; #define XB_SPIN(cond, bar) do { unsigned _sp = 0; while (cond) { __builtin_amdgcn_s_sleep(1); \
;     if ((++_sp & 255u) == 0u) { if (xb_ld(&(bar)[XB_TMO])) break; if (_sp > XB_SPIN_CAP) { atomicAdd(&(bar)[XB_TMO], 1u); break; } } } } while (0)
; __device__ __forceinline__ void xcd_barrier(const XcdBarrier& b) {
;     ...
;             XB_SPIN(xb_ld(&bar[XB_XGEN(b.x)]) == gen, bar);
.LBB0_140:
	global_load_dword v3, v1, s[10:11] sc1
	s_add_i32 s24, s24, 1
	s_mov_b64 s[20:21], -1
	s_waitcnt vmcnt(0)
	v_cmp_ge_u32_e32 vcc, v3, v2
	s_orn2_b64 s[18:19], vcc, exec
	s_branch .LBB0_137

; __device__ __forceinline__ unsigned xb_ld(unsigned* p)              { return __hip_atomic_load(p, __ATOMIC_RELAXED, __HIP_MEMORY_SCOPE_AGENT); }
; __device__ __forceinline__ unsigned xb_add(unsigned* p, unsigned v) { return __hip_atomic_fetch_add(p, v, __ATOMIC_RELAXED, __HIP_MEMORY_SCOPE_AGENT); }
; #define XB_SPIN(cond, bar) do { unsigned _sp = 0; while (cond) { __builtin_amdgcn_s_sleep(1); \
;     if ((++_sp & 255u) == 0u) { if (xb_ld(&(bar)[XB_TMO])) break; if (_sp > XB_SPIN_CAP) { atomicAdd(&(bar)[XB_TMO], 1u); break; } } } } while (0)
; __device__ __forceinline__ void xcd_barrier(const XcdBarrier& b) {
;     ...
;             __builtin_amdgcn_fence(__ATOMIC_RELEASE, "agent");
;             asm volatile("s_waitcnt vmcnt(0)" ::: "memory");
;             const unsigned og = xb_add(&bar[XB_TOP], 1u);
;             const unsigned tg = og / nx;
;             if (og + 1u == (tg + 1u) * nx) xb_add(&bar[XB_TOPGEN], 1u);
;             else XB_SPIN(xb_ld(&bar[XB_TOPGEN]) == tg, bar);
.LBB0_151:
	s_or_b64 exec, exec, s[8:9]
	v_cvt_f32_u32_e32 v4, v1
	s_waitcnt vmcnt(0)
	v_readfirstlane_b32 s6, v3
	s_mov_b64 s[10:11], -1
	v_rcp_iflag_f32_e32 v4, v4
	v_add_u32_e32 v2, s6, v2
	v_add_u32_e32 v5, 1, v2
	v_readlane_b32 s6, v254, 7
	v_mul_f32_e32 v3, 0x4f7ffffe, v4
	v_cvt_u32_f32_e32 v3, v3
	v_sub_u32_e32 v4, 0, v1
	v_readlane_b32 s7, v254, 8
	s_add_u32 s8, s6, 0x3500
	v_mul_lo_u32 v4, v4, v3
	v_mul_hi_u32 v4, v3, v4
	v_add_u32_e32 v3, v3, v4
	v_mul_hi_u32 v3, v2, v3
	v_mul_lo_u32 v4, v3, v1
	v_sub_u32_e32 v2, v2, v4
	v_add_u32_e32 v6, 1, v3
	v_cmp_ge_u32_e32 vcc, v2, v1
	v_sub_u32_e32 v4, v2, v1
	s_addc_u32 s9, s7, 0
	v_cndmask_b32_e32 v3, v3, v6, vcc
	v_cndmask_b32_e32 v2, v2, v4, vcc
	v_add_u32_e32 v4, 1, v3
	v_cmp_ge_u32_e32 vcc, v2, v1
	s_nop 1
	v_cndmask_b32_e32 v4, v3, v4, vcc
	v_mul_lo_u32 v2, v1, v4
	v_add_u32_e32 v1, v2, v1
	v_mov_b32_e32 v4, v1
	v_cmp_ne_u32_e32 vcc, v5, v1
	v_mov_b64_e32 v[2:3], s[8:9]
	s_and_saveexec_b64 s[6:7], vcc
	s_cbranch_execz .LBB0_163
	v_mov_b32_e32 v1, 0
	global_load_dword v2, v1, s[8:9] offset:-256 sc1
	s_mov_b64 s[16:17], 0
	s_waitcnt vmcnt(0)
	v_cmp_lt_u32_e32 vcc, v2, v4
	s_and_saveexec_b64 s[14:15], vcc
	s_cbranch_execz .LBB0_162
	v_readlane_b32 s10, v254, 7
	v_readlane_b32 s11, v254, 8
	s_add_u32 s10, s10, 0x200
	s_addc_u32 s11, s11, 0
	s_mov_b32 s26, 1
	s_branch .LBB0_155

; __device__ __forceinline__ unsigned xb_ld(unsigned* p)              { return __hip_atomic_load(p, __ATOMIC_RELAXED, __HIP_MEMORY_SCOPE_AGENT); }
; #define XB_SPIN(cond, bar) do { unsigned _sp = 0; while (cond) { __builtin_amdgcn_s_sleep(1); \
;     if ((++_sp & 255u) == 0u) { if (xb_ld(&(bar)[XB_TMO])) break; if (_sp > XB_SPIN_CAP) { atomicAdd(&(bar)[XB_TMO], 1u); break; } } } } while (0)
; __device__ __forceinline__ void xcd_barrier(const XcdBarrier& b) {
;     ...
;             else XB_SPIN(xb_ld(&bar[XB_TOPGEN]) == tg, bar);
.LBB0_157:
	global_load_dword v2, v1, s[8:9] offset:-256 sc1
	s_add_i32 s26, s26, 1
	s_mov_b64 s[20:21], -1
	s_waitcnt vmcnt(0)
	v_cmp_ge_u32_e32 vcc, v2, v4
	s_orn2_b64 s[24:25], vcc, exec
	s_branch .LBB0_154

; __device__ __forceinline__ unsigned xb_ld(unsigned* p)              { return __hip_atomic_load(p, __ATOMIC_RELAXED, __HIP_MEMORY_SCOPE_AGENT); }
; __device__ __forceinline__ unsigned xb_add(unsigned* p, unsigned v) { return __hip_atomic_fetch_add(p, v, __ATOMIC_RELAXED, __HIP_MEMORY_SCOPE_AGENT); }
; #define XB_SPIN(cond, bar) do { unsigned _sp = 0; while (cond) { __builtin_amdgcn_s_sleep(1); \
;     if ((++_sp & 255u) == 0u) { if (xb_ld(&(bar)[XB_TMO])) break; if (_sp > XB_SPIN_CAP) { atomicAdd(&(bar)[XB_TMO], 1u); break; } } } } while (0)
; __device__ __forceinline__ void xcd_barrier(const XcdBarrier& b) {
;     ...
;         const unsigned old = xb_add(&bar[XB_XSUB(b.x)], 1u);
;         const unsigned gen = old / nloc;
;         if (old + 1u == (gen + 1u) * nloc) {
;             __builtin_amdgcn_fence(__ATOMIC_RELEASE, "agent");
;             asm volatile("s_waitcnt vmcnt(0)" ::: "memory");
;             const unsigned og = xb_add(&bar[XB_TOP], 1u);
;             const unsigned tg = og / nx;
;             if (og + 1u == (tg + 1u) * nx) xb_add(&bar[XB_TOPGEN], 1u);
;             else XB_SPIN(xb_ld(&bar[XB_TOPGEN]) == tg, bar);
;             __builtin_amdgcn_fence(__ATOMIC_ACQUIRE, "agent");
;             xb_add(&bar[XB_XGEN(b.x)], 1u);
;             asm volatile("s_waitcnt vmcnt(0)" ::: "memory");
;         } else {
;             XB_SPIN(xb_ld(&bar[XB_XGEN(b.x)]) == gen, bar);
;             __builtin_amdgcn_fence(__ATOMIC_ACQUIRE, "agent");
;             asm volatile("s_waitcnt vmcnt(0)" ::: "memory");
;         }
.LBB0_624:
	v_readlane_b32 s4, v254, 9
	s_lshl_b32 s4, s4, 8
	v_readlane_b32 s6, v254, 7
	v_readlane_b32 s7, v254, 8
	s_add_u32 s4, s6, s4
	s_addc_u32 s5, s7, 0
	v_mov_b32_e32 v2, 0x1000
	v_mov_b32_e32 v4, 1
	global_atomic_add v4, v2, v4, s[4:5] offset:1024 sc0
	v_cvt_f32_u32_e32 v2, v3
	v_sub_u32_e32 v5, 0, v3
	v_rcp_iflag_f32_e32 v2, v2
	s_nop 0
	v_mul_f32_e32 v2, 0x4f7ffffe, v2
	v_cvt_u32_f32_e32 v2, v2
	v_mul_lo_u32 v5, v5, v2
	v_mul_hi_u32 v5, v2, v5
	v_add_u32_e32 v2, v2, v5
	s_waitcnt vmcnt(0)
	v_mul_hi_u32 v2, v4, v2
	v_mul_lo_u32 v5, v2, v3
	v_sub_u32_e32 v5, v4, v5
	v_add_u32_e32 v6, 1, v2
	v_cmp_ge_u32_e32 vcc, v5, v3
	v_add_u32_e32 v4, 1, v4
	s_nop 0
	v_cndmask_b32_e32 v2, v2, v6, vcc
	v_sub_u32_e32 v6, v5, v3
	v_cndmask_b32_e32 v5, v5, v6, vcc
	v_add_u32_e32 v6, 1, v2
	v_cmp_ge_u32_e32 vcc, v5, v3
	s_nop 1
	v_cndmask_b32_e32 v2, v2, v6, vcc
	v_mul_lo_u32 v5, v3, v2
	v_add_u32_e32 v3, v5, v3
	v_cmp_ne_u32_e32 vcc, v4, v3
	s_and_saveexec_b64 s[6:7], vcc
	s_xor_b64 s[6:7], exec, s[6:7]
	s_cbranch_execz .LBB0_638
	s_waitcnt lgkmcnt(0)
	v_readlane_b32 s10, v254, 7
	v_readlane_b32 s11, v254, 8
	v_add_u32_e32 v2, 1, v2
	v_mul_lo_u32 v2, v2, v1
	v_mov_b32_e32 v1, 0
	s_add_u32 s10, s10, 0x3400
	s_addc_u32 s11, s11, 0
	global_load_dword v1, v1, s[10:11] sc1
	s_waitcnt vmcnt(0)
	v_cmp_lt_u32_e32 vcc, v1, v2
	s_and_saveexec_b64 s[8:9], vcc
	s_cbranch_execz .LBB0_637
	s_mov_b32 s22, 1
	s_mov_b64 s[12:13], 0
	v_mov_b32_e32 v1, 0
	s_branch .LBB0_628

; __device__ __forceinline__ unsigned xb_ld(unsigned* p)              { return __hip_atomic_load(p, __ATOMIC_RELAXED, __HIP_MEMORY_SCOPE_AGENT); }
; #define XB_SPIN(cond, bar) do { unsigned _sp = 0; while (cond) { __builtin_amdgcn_s_sleep(1); \
;     if ((++_sp & 255u) == 0u) { if (xb_ld(&(bar)[XB_TMO])) break; if (_sp > XB_SPIN_CAP) { atomicAdd(&(bar)[XB_TMO], 1u); break; } } } } while (0)
; __device__ __forceinline__ void xcd_barrier(const XcdBarrier& b) {
;     ...
;             XB_SPIN(xb_ld(&bar[XB_XGEN(b.x)]) == gen, bar);
.LBB0_630:
	global_load_dword v3, v1, s[10:11] sc1
	s_add_i32 s22, s22, 1
	s_mov_b64 s[18:19], -1
	s_waitcnt vmcnt(0)
	v_cmp_ge_u32_e32 vcc, v3, v2
	s_orn2_b64 s[16:17], vcc, exec
	s_branch .LBB0_627

; __device__ __forceinline__ unsigned xb_ld(unsigned* p)              { return __hip_atomic_load(p, __ATOMIC_RELAXED, __HIP_MEMORY_SCOPE_AGENT); }
; __device__ __forceinline__ unsigned xb_add(unsigned* p, unsigned v) { return __hip_atomic_fetch_add(p, v, __ATOMIC_RELAXED, __HIP_MEMORY_SCOPE_AGENT); }
; #define XB_SPIN(cond, bar) do { unsigned _sp = 0; while (cond) { __builtin_amdgcn_s_sleep(1); \
;     if ((++_sp & 255u) == 0u) { if (xb_ld(&(bar)[XB_TMO])) break; if (_sp > XB_SPIN_CAP) { atomicAdd(&(bar)[XB_TMO], 1u); break; } } } } while (0)
; __device__ __forceinline__ void xcd_barrier(const XcdBarrier& b) {
;     ...
;             __builtin_amdgcn_fence(__ATOMIC_RELEASE, "agent");
;             asm volatile("s_waitcnt vmcnt(0)" ::: "memory");
;             const unsigned og = xb_add(&bar[XB_TOP], 1u);
;             const unsigned tg = og / nx;
;             if (og + 1u == (tg + 1u) * nx) xb_add(&bar[XB_TOPGEN], 1u);
;             else XB_SPIN(xb_ld(&bar[XB_TOPGEN]) == tg, bar);
.LBB0_641:
	s_or_b64 exec, exec, s[8:9]
	v_cvt_f32_u32_e32 v4, v1
	s_waitcnt vmcnt(0)
	v_readfirstlane_b32 s6, v3
	s_mov_b64 s[10:11], -1
	v_rcp_iflag_f32_e32 v4, v4
	v_add_u32_e32 v2, s6, v2
	v_add_u32_e32 v5, 1, v2
	v_readlane_b32 s6, v254, 7
	v_mul_f32_e32 v3, 0x4f7ffffe, v4
	v_cvt_u32_f32_e32 v3, v3
	v_sub_u32_e32 v4, 0, v1
	v_readlane_b32 s7, v254, 8
	s_add_u32 s8, s6, 0x3500
	v_mul_lo_u32 v4, v4, v3
	v_mul_hi_u32 v4, v3, v4
	v_add_u32_e32 v3, v3, v4
	v_mul_hi_u32 v3, v2, v3
	v_mul_lo_u32 v4, v3, v1
	v_sub_u32_e32 v2, v2, v4
	v_add_u32_e32 v6, 1, v3
	v_cmp_ge_u32_e32 vcc, v2, v1
	v_sub_u32_e32 v4, v2, v1
	s_addc_u32 s9, s7, 0
	v_cndmask_b32_e32 v3, v3, v6, vcc
	v_cndmask_b32_e32 v2, v2, v4, vcc
	v_add_u32_e32 v4, 1, v3
	v_cmp_ge_u32_e32 vcc, v2, v1
	s_nop 1
	v_cndmask_b32_e32 v4, v3, v4, vcc
	v_mul_lo_u32 v2, v1, v4
	v_add_u32_e32 v1, v2, v1
	v_mov_b32_e32 v4, v1
	v_cmp_ne_u32_e32 vcc, v5, v1
	v_mov_b64_e32 v[2:3], s[8:9]
	s_and_saveexec_b64 s[6:7], vcc
	s_cbranch_execz .LBB0_653
	v_mov_b32_e32 v1, 0
	global_load_dword v2, v1, s[8:9] offset:-256 sc1
	s_mov_b64 s[14:15], 0
	s_waitcnt vmcnt(0)
	v_cmp_lt_u32_e32 vcc, v2, v4
	s_and_saveexec_b64 s[12:13], vcc
	s_cbranch_execz .LBB0_652
	v_readlane_b32 s10, v254, 7
	v_readlane_b32 s11, v254, 8
	s_add_u32 s10, s10, 0x200
	s_addc_u32 s11, s11, 0
	s_mov_b32 s24, 1
	s_branch .LBB0_645

; __device__ __forceinline__ unsigned xb_ld(unsigned* p)              { return __hip_atomic_load(p, __ATOMIC_RELAXED, __HIP_MEMORY_SCOPE_AGENT); }
; #define XB_SPIN(cond, bar) do { unsigned _sp = 0; while (cond) { __builtin_amdgcn_s_sleep(1); \
;     if ((++_sp & 255u) == 0u) { if (xb_ld(&(bar)[XB_TMO])) break; if (_sp > XB_SPIN_CAP) { atomicAdd(&(bar)[XB_TMO], 1u); break; } } } } while (0)
; __device__ __forceinline__ void xcd_barrier(const XcdBarrier& b) {
;     ...
;             else XB_SPIN(xb_ld(&bar[XB_TOPGEN]) == tg, bar);
.LBB0_647:
	global_load_dword v2, v1, s[8:9] offset:-256 sc1
	s_add_i32 s24, s24, 1
	s_mov_b64 s[18:19], -1
	s_waitcnt vmcnt(0)
	v_cmp_ge_u32_e32 vcc, v2, v4
	s_orn2_b64 s[22:23], vcc, exec
	s_branch .LBB0_644

; __device__ __forceinline__ unsigned xb_ld(unsigned* p)              { return __hip_atomic_load(p, __ATOMIC_RELAXED, __HIP_MEMORY_SCOPE_AGENT); }
; __device__ __forceinline__ unsigned xb_add(unsigned* p, unsigned v) { return __hip_atomic_fetch_add(p, v, __ATOMIC_RELAXED, __HIP_MEMORY_SCOPE_AGENT); }
; #define XB_SPIN(cond, bar) do { unsigned _sp = 0; while (cond) { __builtin_amdgcn_s_sleep(1); \
;     if ((++_sp & 255u) == 0u) { if (xb_ld(&(bar)[XB_TMO])) break; if (_sp > XB_SPIN_CAP) { atomicAdd(&(bar)[XB_TMO], 1u); break; } } } } while (0)
; __device__ __forceinline__ void xcd_barrier(const XcdBarrier& b) {
;     ...
;         const unsigned old = xb_add(&bar[XB_XSUB(b.x)], 1u);
;         const unsigned gen = old / nloc;
;         if (old + 1u == (gen + 1u) * nloc) {
;             __builtin_amdgcn_fence(__ATOMIC_RELEASE, "agent");
;             asm volatile("s_waitcnt vmcnt(0)" ::: "memory");
;             const unsigned og = xb_add(&bar[XB_TOP], 1u);
;             const unsigned tg = og / nx;
;             if (og + 1u == (tg + 1u) * nx) xb_add(&bar[XB_TOPGEN], 1u);
;             else XB_SPIN(xb_ld(&bar[XB_TOPGEN]) == tg, bar);
;             __builtin_amdgcn_fence(__ATOMIC_ACQUIRE, "agent");
;             xb_add(&bar[XB_XGEN(b.x)], 1u);
;             asm volatile("s_waitcnt vmcnt(0)" ::: "memory");
;         } else {
;             XB_SPIN(xb_ld(&bar[XB_XGEN(b.x)]) == gen, bar);
;             __builtin_amdgcn_fence(__ATOMIC_ACQUIRE, "agent");
;             asm volatile("s_waitcnt vmcnt(0)" ::: "memory");
;         }
.LBB0_3529:
	v_readlane_b32 s4, v254, 9
	s_lshl_b32 s4, s4, 8
	v_readlane_b32 s6, v254, 7
	v_readlane_b32 s7, v254, 8
	s_add_u32 s4, s6, s4
	s_addc_u32 s5, s7, 0
	v_mov_b32_e32 v1, 0x1000
	v_mov_b32_e32 v3, 1
	global_atomic_add v3, v1, v3, s[4:5] offset:1024 sc0
	v_cvt_f32_u32_e32 v1, v2
	v_sub_u32_e32 v4, 0, v2
	v_rcp_iflag_f32_e32 v1, v1
	s_nop 0
	v_mul_f32_e32 v1, 0x4f7ffffe, v1
	v_cvt_u32_f32_e32 v1, v1
	v_mul_lo_u32 v4, v4, v1
	v_mul_hi_u32 v4, v1, v4
	v_add_u32_e32 v1, v1, v4
	s_waitcnt vmcnt(0)
	v_mul_hi_u32 v1, v3, v1
	v_mul_lo_u32 v4, v1, v2
	v_sub_u32_e32 v4, v3, v4
	v_add_u32_e32 v5, 1, v1
	v_cmp_ge_u32_e32 vcc, v4, v2
	v_add_u32_e32 v3, 1, v3
	s_nop 0
	v_cndmask_b32_e32 v1, v1, v5, vcc
	v_sub_u32_e32 v5, v4, v2
	v_cndmask_b32_e32 v4, v4, v5, vcc
	v_add_u32_e32 v5, 1, v1
	v_cmp_ge_u32_e32 vcc, v4, v2
	s_nop 1
	v_cndmask_b32_e32 v1, v1, v5, vcc
	v_mul_lo_u32 v4, v2, v1
	v_add_u32_e32 v2, v4, v2
	v_cmp_ne_u32_e32 vcc, v3, v2
	s_and_saveexec_b64 s[6:7], vcc
	s_xor_b64 s[6:7], exec, s[6:7]
	s_cbranch_execz .LBB0_3543
	s_waitcnt lgkmcnt(0)
	v_readlane_b32 s10, v254, 7
	v_readlane_b32 s11, v254, 8
	v_add_u32_e32 v1, 1, v1
	v_mul_lo_u32 v1, v1, v0
	v_mov_b32_e32 v0, 0
	s_add_u32 s10, s10, 0x3400
	s_addc_u32 s11, s11, 0
	global_load_dword v0, v0, s[10:11] sc1
	s_waitcnt vmcnt(0)
	v_cmp_lt_u32_e32 vcc, v0, v1
	s_and_saveexec_b64 s[8:9], vcc
	s_cbranch_execz .LBB0_3542
	s_mov_b32 s22, 1
	s_mov_b64 s[12:13], 0
	v_mov_b32_e32 v0, 0
	s_branch .LBB0_3533

; __device__ __forceinline__ unsigned xb_ld(unsigned* p)              { return __hip_atomic_load(p, __ATOMIC_RELAXED, __HIP_MEMORY_SCOPE_AGENT); }
; #define XB_SPIN(cond, bar) do { unsigned _sp = 0; while (cond) { __builtin_amdgcn_s_sleep(1); \
;     if ((++_sp & 255u) == 0u) { if (xb_ld(&(bar)[XB_TMO])) break; if (_sp > XB_SPIN_CAP) { atomicAdd(&(bar)[XB_TMO], 1u); break; } } } } while (0)
; __device__ __forceinline__ void xcd_barrier(const XcdBarrier& b) {
;     ...
;             XB_SPIN(xb_ld(&bar[XB_XGEN(b.x)]) == gen, bar);
.LBB0_3535:
	global_load_dword v2, v0, s[10:11] sc1
	s_add_i32 s22, s22, 1
	s_mov_b64 s[18:19], -1
	s_waitcnt vmcnt(0)
	v_cmp_ge_u32_e32 vcc, v2, v1
	s_orn2_b64 s[16:17], vcc, exec
	s_branch .LBB0_3532

; __device__ __forceinline__ unsigned xb_ld(unsigned* p)              { return __hip_atomic_load(p, __ATOMIC_RELAXED, __HIP_MEMORY_SCOPE_AGENT); }
; __device__ __forceinline__ unsigned xb_add(unsigned* p, unsigned v) { return __hip_atomic_fetch_add(p, v, __ATOMIC_RELAXED, __HIP_MEMORY_SCOPE_AGENT); }
; #define XB_SPIN(cond, bar) do { unsigned _sp = 0; while (cond) { __builtin_amdgcn_s_sleep(1); \
;     if ((++_sp & 255u) == 0u) { if (xb_ld(&(bar)[XB_TMO])) break; if (_sp > XB_SPIN_CAP) { atomicAdd(&(bar)[XB_TMO], 1u); break; } } } } while (0)
; __device__ __forceinline__ void xcd_barrier(const XcdBarrier& b) {
;     ...
;             __builtin_amdgcn_fence(__ATOMIC_RELEASE, "agent");
;             asm volatile("s_waitcnt vmcnt(0)" ::: "memory");
;             const unsigned og = xb_add(&bar[XB_TOP], 1u);
;             const unsigned tg = og / nx;
;             if (og + 1u == (tg + 1u) * nx) xb_add(&bar[XB_TOPGEN], 1u);
;             else XB_SPIN(xb_ld(&bar[XB_TOPGEN]) == tg, bar);
.LBB0_3546:
	s_or_b64 exec, exec, s[8:9]
	v_cvt_f32_u32_e32 v3, v0
	s_waitcnt vmcnt(0)
	v_readfirstlane_b32 s6, v2
	s_mov_b64 s[10:11], -1
	v_rcp_iflag_f32_e32 v3, v3
	v_add_u32_e32 v1, s6, v1
	v_add_u32_e32 v4, 1, v1
	v_readlane_b32 s6, v254, 7
	v_mul_f32_e32 v2, 0x4f7ffffe, v3
	v_cvt_u32_f32_e32 v2, v2
	v_sub_u32_e32 v3, 0, v0
	v_readlane_b32 s7, v254, 8
	s_add_u32 s8, s6, 0x3500
	v_mul_lo_u32 v3, v3, v2
	v_mul_hi_u32 v3, v2, v3
	v_add_u32_e32 v2, v2, v3
	v_mul_hi_u32 v2, v1, v2
	v_mul_lo_u32 v3, v2, v0
	v_sub_u32_e32 v1, v1, v3
	v_add_u32_e32 v5, 1, v2
	v_cmp_ge_u32_e32 vcc, v1, v0
	v_sub_u32_e32 v3, v1, v0
	s_addc_u32 s9, s7, 0
	v_cndmask_b32_e32 v2, v2, v5, vcc
	v_cndmask_b32_e32 v1, v1, v3, vcc
	v_add_u32_e32 v3, 1, v2
	v_cmp_ge_u32_e32 vcc, v1, v0
	s_nop 1
	v_cndmask_b32_e32 v2, v2, v3, vcc
	v_mul_lo_u32 v1, v0, v2
	v_add_u32_e32 v0, v1, v0
	v_mov_b32_e32 v2, v0
	v_cmp_ne_u32_e32 vcc, v4, v0
	v_mov_b64_e32 v[0:1], s[8:9]
	s_and_saveexec_b64 s[6:7], vcc
	s_cbranch_execz .LBB0_3558
	v_mov_b32_e32 v0, 0
	global_load_dword v1, v0, s[8:9] offset:-256 sc1
	s_mov_b64 s[14:15], 0
	s_waitcnt vmcnt(0)
	v_cmp_lt_u32_e32 vcc, v1, v2
	s_and_saveexec_b64 s[12:13], vcc
	s_cbranch_execz .LBB0_3557
	v_readlane_b32 s10, v254, 7
	v_readlane_b32 s11, v254, 8
	s_add_u32 s10, s10, 0x200
	s_addc_u32 s11, s11, 0
	s_mov_b32 s24, 1
	s_branch .LBB0_3550

; __device__ __forceinline__ unsigned xb_ld(unsigned* p)              { return __hip_atomic_load(p, __ATOMIC_RELAXED, __HIP_MEMORY_SCOPE_AGENT); }
; #define XB_SPIN(cond, bar) do { unsigned _sp = 0; while (cond) { __builtin_amdgcn_s_sleep(1); \
;     if ((++_sp & 255u) == 0u) { if (xb_ld(&(bar)[XB_TMO])) break; if (_sp > XB_SPIN_CAP) { atomicAdd(&(bar)[XB_TMO], 1u); break; } } } } while (0)
; __device__ __forceinline__ void xcd_barrier(const XcdBarrier& b) {
;     ...
;             else XB_SPIN(xb_ld(&bar[XB_TOPGEN]) == tg, bar);
.LBB0_3552:
	global_load_dword v1, v0, s[8:9] offset:-256 sc1
	s_add_i32 s24, s24, 1
	s_mov_b64 s[18:19], -1
	s_waitcnt vmcnt(0)
	v_cmp_ge_u32_e32 vcc, v1, v2
	s_orn2_b64 s[22:23], vcc, exec
	s_branch .LBB0_3549
